# seams: leaders skip XGEN forward and release-atomic waits
# speedup vs baseline: 1.0071x; 1.0071x over previous
; __device__ __forceinline__ unsigned xb_ld(unsigned* p)              { return __hip_atomic_load(p, __ATOMIC_RELAXED, __HIP_MEMORY_SCOPE_AGENT); }
; __device__ __forceinline__ unsigned xb_add(unsigned* p, unsigned v) { return __hip_atomic_fetch_add(p, v, __ATOMIC_RELAXED, __HIP_MEMORY_SCOPE_AGENT); }
; #define XB_SPIN(cond, bar) do { unsigned _sp = 0; while (cond) { __builtin_amdgcn_s_sleep(1); \
;     if ((++_sp & 255u) == 0u) { if (xb_ld(&(bar)[XB_TMO])) break; if (_sp > XB_SPIN_CAP) { atomicAdd(&(bar)[XB_TMO], 1u); break; } } } } while (0)
; __device__ __forceinline__ void xcd_barrier(const XcdBarrier& b) {
;     ...
;             if (og + 1u == (tg + 1u) * nx) xb_add(&bar[XB_TOPGEN], 1u);
;             else XB_SPIN(xb_ld(&bar[XB_TOPGEN]) == tg, bar);
;             __builtin_amdgcn_fence(__ATOMIC_ACQUIRE, "agent");
;             xb_add(&bar[XB_XGEN(b.x)], 1u);
;             asm volatile("s_waitcnt vmcnt(0)" ::: "memory");
;         } else {
;             XB_SPIN(xb_ld(&bar[XB_XGEN(b.x)]) == gen, bar);
;             __builtin_amdgcn_fence(__ATOMIC_ACQUIRE, "agent");
;             asm volatile("s_waitcnt vmcnt(0)" ::: "memory");
;         }
;     }
;     __syncthreads();
.LBB0_195:
	s_or_b64 exec, exec, s[6:7]
	s_mov_b64 s[6:7], exec
	v_mbcnt_lo_u32_b32 v0, s6, 0
	v_mbcnt_hi_u32_b32 v0, s7, v0
	v_cmp_eq_u32_e32 vcc, 0, v0
	s_and_saveexec_b64 s[8:9], vcc
	s_cbranch_execz .LBB0_197
	s_bcnt1_i32_b64 s3, s[6:7]
	v_mov_b32_e32 v0, 0x2000
	v_mov_b32_e32 v1, s3
.LBB0_197:
	s_or_b64 exec, exec, s[8:9]
.LBB0_198:
	s_or_b64 exec, exec, s[0:1]
	s_waitcnt lgkmcnt(0)
	s_barrier

; __device__ __forceinline__ unsigned xb_ld(unsigned* p)              { return __hip_atomic_load(p, __ATOMIC_RELAXED, __HIP_MEMORY_SCOPE_AGENT); }
; __device__ __forceinline__ unsigned xb_add(unsigned* p, unsigned v) { return __hip_atomic_fetch_add(p, v, __ATOMIC_RELAXED, __HIP_MEMORY_SCOPE_AGENT); }
; #define XB_SPIN(cond, bar) do { unsigned _sp = 0; while (cond) { __builtin_amdgcn_s_sleep(1); \
;     if ((++_sp & 255u) == 0u) { if (xb_ld(&(bar)[XB_TMO])) break; if (_sp > XB_SPIN_CAP) { atomicAdd(&(bar)[XB_TMO], 1u); break; } } } } while (0)
; __device__ __forceinline__ void xcd_barrier(const XcdBarrier& b) {
;     ...
;             if (og + 1u == (tg + 1u) * nx) xb_add(&bar[XB_TOPGEN], 1u);
;             else XB_SPIN(xb_ld(&bar[XB_TOPGEN]) == tg, bar);
;             __builtin_amdgcn_fence(__ATOMIC_ACQUIRE, "agent");
;             xb_add(&bar[XB_XGEN(b.x)], 1u);
;             asm volatile("s_waitcnt vmcnt(0)" ::: "memory");
;         } else {
;             XB_SPIN(xb_ld(&bar[XB_XGEN(b.x)]) == gen, bar);
;             __builtin_amdgcn_fence(__ATOMIC_ACQUIRE, "agent");
;             asm volatile("s_waitcnt vmcnt(0)" ::: "memory");
;         }
;     }
;     __syncthreads();
.LBB0_496:
	s_or_b64 exec, exec, s[8:9]
.LBB0_497:
	s_or_b64 exec, exec, s[0:1]
	s_waitcnt lgkmcnt(0)
	s_barrier

; __device__ __forceinline__ unsigned xb_ld(unsigned* p)              { return __hip_atomic_load(p, __ATOMIC_RELAXED, __HIP_MEMORY_SCOPE_AGENT); }
; __device__ __forceinline__ unsigned xb_add(unsigned* p, unsigned v) { return __hip_atomic_fetch_add(p, v, __ATOMIC_RELAXED, __HIP_MEMORY_SCOPE_AGENT); }
; #define XB_SPIN(cond, bar) do { unsigned _sp = 0; while (cond) { __builtin_amdgcn_s_sleep(1); \
;     if ((++_sp & 255u) == 0u) { if (xb_ld(&(bar)[XB_TMO])) break; if (_sp > XB_SPIN_CAP) { atomicAdd(&(bar)[XB_TMO], 1u); break; } } } } while (0)
; __device__ __forceinline__ void xcd_barrier(const XcdBarrier& b) {
;     ...
;             if (og + 1u == (tg + 1u) * nx) xb_add(&bar[XB_TOPGEN], 1u);
;             else XB_SPIN(xb_ld(&bar[XB_TOPGEN]) == tg, bar);
;             __builtin_amdgcn_fence(__ATOMIC_ACQUIRE, "agent");
;             xb_add(&bar[XB_XGEN(b.x)], 1u);
;             asm volatile("s_waitcnt vmcnt(0)" ::: "memory");
;         } else {
;             XB_SPIN(xb_ld(&bar[XB_XGEN(b.x)]) == gen, bar);
;             __builtin_amdgcn_fence(__ATOMIC_ACQUIRE, "agent");
;             asm volatile("s_waitcnt vmcnt(0)" ::: "memory");
;         }
;     }
;     __syncthreads();
.LBB0_628:
	s_or_b64 exec, exec, s[8:9]
	s_mov_b64 s[8:9], exec
	v_mbcnt_lo_u32_b32 v0, s8, 0
	v_mbcnt_hi_u32_b32 v0, s9, v0
	v_cmp_eq_u32_e32 vcc, 0, v0
	s_and_saveexec_b64 s[10:11], vcc
	s_cbranch_execz .LBB0_630
	s_bcnt1_i32_b64 s3, s[8:9]
	v_mov_b32_e32 v0, 0x2000
	v_mov_b32_e32 v1, s3
.LBB0_630:
	s_or_b64 exec, exec, s[10:11]
.LBB0_631:
	s_or_b64 exec, exec, s[4:5]
	s_waitcnt lgkmcnt(0)
	s_barrier
	s_cmp_lt_i32 s2, 16
	s_mov_b64 s[4:5], -1
	s_cbranch_scc0 .LBB0_559

; __device__ __forceinline__ unsigned xb_ld(unsigned* p)              { return __hip_atomic_load(p, __ATOMIC_RELAXED, __HIP_MEMORY_SCOPE_AGENT); }
; __device__ __forceinline__ unsigned xb_add(unsigned* p, unsigned v) { return __hip_atomic_fetch_add(p, v, __ATOMIC_RELAXED, __HIP_MEMORY_SCOPE_AGENT); }
; #define XB_SPIN(cond, bar) do { unsigned _sp = 0; while (cond) { __builtin_amdgcn_s_sleep(1); \
;     if ((++_sp & 255u) == 0u) { if (xb_ld(&(bar)[XB_TMO])) break; if (_sp > XB_SPIN_CAP) { atomicAdd(&(bar)[XB_TMO], 1u); break; } } } } while (0)
; __device__ __forceinline__ void xcd_barrier(const XcdBarrier& b) {
;     ...
;             if (og + 1u == (tg + 1u) * nx) xb_add(&bar[XB_TOPGEN], 1u);
;             else XB_SPIN(xb_ld(&bar[XB_TOPGEN]) == tg, bar);
;             __builtin_amdgcn_fence(__ATOMIC_ACQUIRE, "agent");
;             xb_add(&bar[XB_XGEN(b.x)], 1u);
;             asm volatile("s_waitcnt vmcnt(0)" ::: "memory");
;         } else {
;             XB_SPIN(xb_ld(&bar[XB_XGEN(b.x)]) == gen, bar);
;             __builtin_amdgcn_fence(__ATOMIC_ACQUIRE, "agent");
;             asm volatile("s_waitcnt vmcnt(0)" ::: "memory");
;         }
;     }
;     __syncthreads();
.LBB0_723:
	s_or_b64 exec, exec, s[8:9]
.LBB0_724:
	s_or_b64 exec, exec, s[0:1]
	s_waitcnt lgkmcnt(0)
	s_barrier

; __device__ __forceinline__ unsigned xb_ld(unsigned* p)              { return __hip_atomic_load(p, __ATOMIC_RELAXED, __HIP_MEMORY_SCOPE_AGENT); }
; __device__ __forceinline__ unsigned xb_add(unsigned* p, unsigned v) { return __hip_atomic_fetch_add(p, v, __ATOMIC_RELAXED, __HIP_MEMORY_SCOPE_AGENT); }
; #define XB_SPIN(cond, bar) do { unsigned _sp = 0; while (cond) { __builtin_amdgcn_s_sleep(1); \
;     if ((++_sp & 255u) == 0u) { if (xb_ld(&(bar)[XB_TMO])) break; if (_sp > XB_SPIN_CAP) { atomicAdd(&(bar)[XB_TMO], 1u); break; } } } } while (0)
; __device__ __forceinline__ void xcd_barrier(const XcdBarrier& b) {
;     ...
;             if (og + 1u == (tg + 1u) * nx) xb_add(&bar[XB_TOPGEN], 1u);
;             else XB_SPIN(xb_ld(&bar[XB_TOPGEN]) == tg, bar);
;             __builtin_amdgcn_fence(__ATOMIC_ACQUIRE, "agent");
;             xb_add(&bar[XB_XGEN(b.x)], 1u);
;             asm volatile("s_waitcnt vmcnt(0)" ::: "memory");
;         } else {
;             XB_SPIN(xb_ld(&bar[XB_XGEN(b.x)]) == gen, bar);
;             __builtin_amdgcn_fence(__ATOMIC_ACQUIRE, "agent");
;             asm volatile("s_waitcnt vmcnt(0)" ::: "memory");
;         }
;     }
;     __syncthreads();
.LBB0_798:
	s_or_b64 exec, exec, s[8:9]
.LBB0_799:
	s_or_b64 exec, exec, s[0:1]
	s_waitcnt lgkmcnt(0)
	s_barrier

; __device__ __forceinline__ unsigned xb_ld(unsigned* p)              { return __hip_atomic_load(p, __ATOMIC_RELAXED, __HIP_MEMORY_SCOPE_AGENT); }
; __device__ __forceinline__ unsigned xb_add(unsigned* p, unsigned v) { return __hip_atomic_fetch_add(p, v, __ATOMIC_RELAXED, __HIP_MEMORY_SCOPE_AGENT); }
; #define XB_SPIN(cond, bar) do { unsigned _sp = 0; while (cond) { __builtin_amdgcn_s_sleep(1); \
;     if ((++_sp & 255u) == 0u) { if (xb_ld(&(bar)[XB_TMO])) break; if (_sp > XB_SPIN_CAP) { atomicAdd(&(bar)[XB_TMO], 1u); break; } } } } while (0)
; __device__ __forceinline__ void xcd_barrier(const XcdBarrier& b) {
;     ...
;             if (og + 1u == (tg + 1u) * nx) xb_add(&bar[XB_TOPGEN], 1u);
;             else XB_SPIN(xb_ld(&bar[XB_TOPGEN]) == tg, bar);
;             __builtin_amdgcn_fence(__ATOMIC_ACQUIRE, "agent");
;             xb_add(&bar[XB_XGEN(b.x)], 1u);
;             asm volatile("s_waitcnt vmcnt(0)" ::: "memory");
;         } else {
;             XB_SPIN(xb_ld(&bar[XB_XGEN(b.x)]) == gen, bar);
;             __builtin_amdgcn_fence(__ATOMIC_ACQUIRE, "agent");
;             asm volatile("s_waitcnt vmcnt(0)" ::: "memory");
;         }
;     }
;     __syncthreads();
.LBB0_894:
	s_or_b64 exec, exec, s[10:11]
.LBB0_895:
	s_or_b64 exec, exec, s[0:1]
	s_waitcnt lgkmcnt(0)
	s_barrier

; __device__ __forceinline__ unsigned xb_ld(unsigned* p)              { return __hip_atomic_load(p, __ATOMIC_RELAXED, __HIP_MEMORY_SCOPE_AGENT); }
; __device__ __forceinline__ unsigned xb_add(unsigned* p, unsigned v) { return __hip_atomic_fetch_add(p, v, __ATOMIC_RELAXED, __HIP_MEMORY_SCOPE_AGENT); }
; #define XB_SPIN(cond, bar) do { unsigned _sp = 0; while (cond) { __builtin_amdgcn_s_sleep(1); \
;     if ((++_sp & 255u) == 0u) { if (xb_ld(&(bar)[XB_TMO])) break; if (_sp > XB_SPIN_CAP) { atomicAdd(&(bar)[XB_TMO], 1u); break; } } } } while (0)
; __device__ __forceinline__ void xcd_barrier(const XcdBarrier& b) {
;     ...
;             if (og + 1u == (tg + 1u) * nx) xb_add(&bar[XB_TOPGEN], 1u);
;             else XB_SPIN(xb_ld(&bar[XB_TOPGEN]) == tg, bar);
;             __builtin_amdgcn_fence(__ATOMIC_ACQUIRE, "agent");
;             xb_add(&bar[XB_XGEN(b.x)], 1u);
;             asm volatile("s_waitcnt vmcnt(0)" ::: "memory");
;         } else {
;             XB_SPIN(xb_ld(&bar[XB_XGEN(b.x)]) == gen, bar);
;             __builtin_amdgcn_fence(__ATOMIC_ACQUIRE, "agent");
;             asm volatile("s_waitcnt vmcnt(0)" ::: "memory");
;         }
;     }
;     __syncthreads();
.LBB0_987:
	s_or_b64 exec, exec, s[10:11]
.LBB0_988:
	s_or_b64 exec, exec, s[0:1]
	s_waitcnt lgkmcnt(0)
	s_barrier

; __device__ __forceinline__ unsigned xb_ld(unsigned* p)              { return __hip_atomic_load(p, __ATOMIC_RELAXED, __HIP_MEMORY_SCOPE_AGENT); }
; __device__ __forceinline__ unsigned xb_add(unsigned* p, unsigned v) { return __hip_atomic_fetch_add(p, v, __ATOMIC_RELAXED, __HIP_MEMORY_SCOPE_AGENT); }
; #define XB_SPIN(cond, bar) do { unsigned _sp = 0; while (cond) { __builtin_amdgcn_s_sleep(1); \
;     if ((++_sp & 255u) == 0u) { if (xb_ld(&(bar)[XB_TMO])) break; if (_sp > XB_SPIN_CAP) { atomicAdd(&(bar)[XB_TMO], 1u); break; } } } } while (0)
; __device__ __forceinline__ void xcd_barrier(const XcdBarrier& b) {
;     ...
;             if (og + 1u == (tg + 1u) * nx) xb_add(&bar[XB_TOPGEN], 1u);
;             else XB_SPIN(xb_ld(&bar[XB_TOPGEN]) == tg, bar);
;             __builtin_amdgcn_fence(__ATOMIC_ACQUIRE, "agent");
;             xb_add(&bar[XB_XGEN(b.x)], 1u);
;             asm volatile("s_waitcnt vmcnt(0)" ::: "memory");
;         } else {
;             XB_SPIN(xb_ld(&bar[XB_XGEN(b.x)]) == gen, bar);
;             __builtin_amdgcn_fence(__ATOMIC_ACQUIRE, "agent");
;             asm volatile("s_waitcnt vmcnt(0)" ::: "memory");
;         }
;     }
;     __syncthreads();
.LBB0_1132:
	s_or_b64 exec, exec, s[10:11]
.LBB0_1133:
	s_or_b64 exec, exec, s[0:1]
	s_waitcnt lgkmcnt(0)
	s_barrier

; __device__ __forceinline__ unsigned xb_ld(unsigned* p)              { return __hip_atomic_load(p, __ATOMIC_RELAXED, __HIP_MEMORY_SCOPE_AGENT); }
; __device__ __forceinline__ unsigned xb_add(unsigned* p, unsigned v) { return __hip_atomic_fetch_add(p, v, __ATOMIC_RELAXED, __HIP_MEMORY_SCOPE_AGENT); }
; #define XB_SPIN(cond, bar) do { unsigned _sp = 0; while (cond) { __builtin_amdgcn_s_sleep(1); \
;     if ((++_sp & 255u) == 0u) { if (xb_ld(&(bar)[XB_TMO])) break; if (_sp > XB_SPIN_CAP) { atomicAdd(&(bar)[XB_TMO], 1u); break; } } } } while (0)
; __device__ __forceinline__ void xcd_barrier(const XcdBarrier& b) {
;     ...
;             if (og + 1u == (tg + 1u) * nx) xb_add(&bar[XB_TOPGEN], 1u);
;             else XB_SPIN(xb_ld(&bar[XB_TOPGEN]) == tg, bar);
;             __builtin_amdgcn_fence(__ATOMIC_ACQUIRE, "agent");
;             xb_add(&bar[XB_XGEN(b.x)], 1u);
;             asm volatile("s_waitcnt vmcnt(0)" ::: "memory");
;         } else {
;             XB_SPIN(xb_ld(&bar[XB_XGEN(b.x)]) == gen, bar);
;             __builtin_amdgcn_fence(__ATOMIC_ACQUIRE, "agent");
;             asm volatile("s_waitcnt vmcnt(0)" ::: "memory");
;         }
;     }
;     __syncthreads();
.LBB0_1192:
	s_or_b64 exec, exec, s[10:11]
.LBB0_1193:
	s_or_b64 exec, exec, s[0:1]
	s_waitcnt lgkmcnt(0)
	s_barrier

; __device__ __forceinline__ unsigned xb_ld(unsigned* p)              { return __hip_atomic_load(p, __ATOMIC_RELAXED, __HIP_MEMORY_SCOPE_AGENT); }
; __device__ __forceinline__ unsigned xb_add(unsigned* p, unsigned v) { return __hip_atomic_fetch_add(p, v, __ATOMIC_RELAXED, __HIP_MEMORY_SCOPE_AGENT); }
; #define XB_SPIN(cond, bar) do { unsigned _sp = 0; while (cond) { __builtin_amdgcn_s_sleep(1); \
;     if ((++_sp & 255u) == 0u) { if (xb_ld(&(bar)[XB_TMO])) break; if (_sp > XB_SPIN_CAP) { atomicAdd(&(bar)[XB_TMO], 1u); break; } } } } while (0)
; __device__ __forceinline__ void xcd_barrier(const XcdBarrier& b) {
;     ...
;             if (og + 1u == (tg + 1u) * nx) xb_add(&bar[XB_TOPGEN], 1u);
;             else XB_SPIN(xb_ld(&bar[XB_TOPGEN]) == tg, bar);
;             __builtin_amdgcn_fence(__ATOMIC_ACQUIRE, "agent");
;             xb_add(&bar[XB_XGEN(b.x)], 1u);
;             asm volatile("s_waitcnt vmcnt(0)" ::: "memory");
;         } else {
;             XB_SPIN(xb_ld(&bar[XB_XGEN(b.x)]) == gen, bar);
;             __builtin_amdgcn_fence(__ATOMIC_ACQUIRE, "agent");
;             asm volatile("s_waitcnt vmcnt(0)" ::: "memory");
;         }
;     }
;     __syncthreads();
.LBB0_1263:
	s_or_b64 exec, exec, s[8:9]
.LBB0_1264:
	s_or_b64 exec, exec, s[0:1]
	s_waitcnt lgkmcnt(0)
	s_barrier

; __device__ __forceinline__ unsigned xb_ld(unsigned* p)              { return __hip_atomic_load(p, __ATOMIC_RELAXED, __HIP_MEMORY_SCOPE_AGENT); }
; __device__ __forceinline__ unsigned xb_add(unsigned* p, unsigned v) { return __hip_atomic_fetch_add(p, v, __ATOMIC_RELAXED, __HIP_MEMORY_SCOPE_AGENT); }
; #define XB_SPIN(cond, bar) do { unsigned _sp = 0; while (cond) { __builtin_amdgcn_s_sleep(1); \
;     if ((++_sp & 255u) == 0u) { if (xb_ld(&(bar)[XB_TMO])) break; if (_sp > XB_SPIN_CAP) { atomicAdd(&(bar)[XB_TMO], 1u); break; } } } } while (0)
; __device__ __forceinline__ void xcd_barrier(const XcdBarrier& b) {
;     ...
;             if (og + 1u == (tg + 1u) * nx) xb_add(&bar[XB_TOPGEN], 1u);
;             else XB_SPIN(xb_ld(&bar[XB_TOPGEN]) == tg, bar);
;             __builtin_amdgcn_fence(__ATOMIC_ACQUIRE, "agent");
;             xb_add(&bar[XB_XGEN(b.x)], 1u);
;             asm volatile("s_waitcnt vmcnt(0)" ::: "memory");
;         } else {
;             XB_SPIN(xb_ld(&bar[XB_XGEN(b.x)]) == gen, bar);
;             __builtin_amdgcn_fence(__ATOMIC_ACQUIRE, "agent");
;             asm volatile("s_waitcnt vmcnt(0)" ::: "memory");
;         }
;     }
;     __syncthreads();
.LBB0_1360:
	s_or_b64 exec, exec, s[10:11]
.LBB0_1361:
	s_or_b64 exec, exec, s[0:1]
	s_waitcnt lgkmcnt(0)
	s_barrier

; __device__ __forceinline__ unsigned xb_ld(unsigned* p)              { return __hip_atomic_load(p, __ATOMIC_RELAXED, __HIP_MEMORY_SCOPE_AGENT); }
; __device__ __forceinline__ unsigned xb_add(unsigned* p, unsigned v) { return __hip_atomic_fetch_add(p, v, __ATOMIC_RELAXED, __HIP_MEMORY_SCOPE_AGENT); }
; #define XB_SPIN(cond, bar) do { unsigned _sp = 0; while (cond) { __builtin_amdgcn_s_sleep(1); \
;     if ((++_sp & 255u) == 0u) { if (xb_ld(&(bar)[XB_TMO])) break; if (_sp > XB_SPIN_CAP) { atomicAdd(&(bar)[XB_TMO], 1u); break; } } } } while (0)
; __device__ __forceinline__ void xcd_barrier(const XcdBarrier& b) {
;     ...
;             if (og + 1u == (tg + 1u) * nx) xb_add(&bar[XB_TOPGEN], 1u);
;             else XB_SPIN(xb_ld(&bar[XB_TOPGEN]) == tg, bar);
;             __builtin_amdgcn_fence(__ATOMIC_ACQUIRE, "agent");
;             xb_add(&bar[XB_XGEN(b.x)], 1u);
;             asm volatile("s_waitcnt vmcnt(0)" ::: "memory");
;         } else {
;             XB_SPIN(xb_ld(&bar[XB_XGEN(b.x)]) == gen, bar);
;             __builtin_amdgcn_fence(__ATOMIC_ACQUIRE, "agent");
;             asm volatile("s_waitcnt vmcnt(0)" ::: "memory");
;         }
;     }
;     __syncthreads();
.LBB0_1513:
	s_or_b64 exec, exec, s[8:9]
.LBB0_1514:
	s_or_b64 exec, exec, s[0:1]
	s_waitcnt lgkmcnt(0)
	s_barrier
